# compress-phase k-loop: all 8 LDS fragment reads issued up front with counted lgkmcnt waits
# baseline (speedup 1.0000x reference)
; #define LAS __attribute__((address_space(3)))
; #define MFMA32(a, b, c) __builtin_amdgcn_mfma_f32_32x32x16_bf16((a), (b), (c), 0, 0, 0)
; #define CMP_LOADB(BR, L) do { _Pragma("unroll") for (int k = 0; k < 4; ++k) { const int id = tid + 512 * k; BR[k] = *(const u32x4*)(bbase + (size_t)(id >> 3) * 2048 + (L) * 64 + (id & 7) * 8); } } while (0)
; __device__ __forceinline__ void compress_phase(const bf16* P, const bf16* W1T  , const float* cmpb  , const float* W2  ,
;                                                bf16* kcmp, bf16* vcmpT, lds_u8* lds, int G, int bid, int tid) {
;     ...
;         for (int l0 = 0; l0 < 32; l0 += 2) {
; #pragma unroll
;             for (int hh = 0; hh < 2; ++hh) { const int l = l0 + hh;
;                 u32x4 (&br)[4] = hh ? brB : brA;
;                 lds_u8* Bb = lds + CB + hh * CBSZ;
; #pragma unroll
;                 for (int k = 0; k < 4; ++k) { const int id = tid + 512 * k; const int col = id >> 3, c = id & 7;
;                     *(LAS u32x4*)(Bb + col * 128 + ((c ^ ((col >> 1) & 7)) * 16)) = br[k]; }
;                 __syncthreads();
;                 if (l + 2 < 32) CMP_LOADB(br, l + 2);
;                 const int arow = 16 * r32 + l;
;                 const lds_u8* ap = lds + CA + arow * 128; const int akey = (arow >> 4) & 7;
;                 const lds_u8* bp = Bb + acol * 128; const int bkey = (acol >> 1) & 7;
; #pragma unroll
;                 for (int ks = 0; ks < 4; ++ks) {
;                     const bf16x8 a = *(const LAS bf16x8*)(ap + (((2 * ks + hi) ^ akey) * 16)), bb = *(const LAS bf16x8*)(bp + (((2 * ks + hi) ^ bkey) * 16));
;                     acc = MFMA32(a, bb, acc);
;                 }
.LBB0_650:
	v_add_u32_e32 v122, 1, v158
	v_and_b32_e32 v158, 0x70, v122
	v_xad_u32 v122, v158, v89, v2
	ds_read_b128 v[122:125], v122 offset:128
	v_add_u32_e32 v126, v143, v93
	ds_read_b128 v[126:129], v126
	v_xad_u32 v159, v158, v95, v2
	ds_read_b128 v[204:207], v159 offset:128
	v_add_u32_e32 v159, v143, v138
	ds_read_b128 v[208:211], v159
	v_xad_u32 v159, v158, v139, v2
	ds_read_b128 v[212:215], v159 offset:128
	v_add_u32_e32 v159, v143, v140
	ds_read_b128 v[216:219], v159
	v_xad_u32 v158, v158, v141, v2
	ds_read_b128 v[236:239], v158 offset:128
	v_add_u32_e32 v159, v143, v142
	ds_read_b128 v[240:243], v159
	v_add_u32_e32 v2, 0x100, v2
	s_add_i32 s21, s21, 2
	v_lshl_add_u64 v[114:115], v[114:115], 0, s[92:93]
	v_lshl_add_u64 v[116:117], v[116:117], 0, s[92:93]
	v_lshl_add_u64 v[118:119], v[118:119], 0, s[92:93]
	v_lshl_add_u64 v[120:121], v[120:121], 0, s[92:93]
	s_and_b64 vcc, exec, s[22:23]
	s_waitcnt lgkmcnt(6)
	v_mfma_f32_32x32x16_bf16 v[4:19], v[122:125], v[126:129], v[4:19]
	s_waitcnt lgkmcnt(4)
	v_mfma_f32_32x32x16_bf16 v[4:19], v[204:207], v[208:211], v[4:19]
	s_waitcnt lgkmcnt(2)
	v_mfma_f32_32x32x16_bf16 v[4:19], v[212:215], v[216:219], v[4:19]
	s_waitcnt lgkmcnt(0)
	v_mfma_f32_32x32x16_bf16 v[4:19], v[236:239], v[240:243], v[4:19]
	s_cbranch_vccnz .LBB0_655

; #define LAS __attribute__((address_space(3)))
; #define MFMA32(a, b, c) __builtin_amdgcn_mfma_f32_32x32x16_bf16((a), (b), (c), 0, 0, 0)
; #define CMP_LOADB(BR, L) do { _Pragma("unroll") for (int k = 0; k < 4; ++k) { const int id = tid + 512 * k; BR[k] = *(const u32x4*)(bbase + (size_t)(id >> 3) * 2048 + (L) * 64 + (id & 7) * 8); } } while (0)
; __device__ __forceinline__ void compress_phase(const bf16* P, const bf16* W1T  , const float* cmpb  , const float* W2  ,
;                                                bf16* kcmp, bf16* vcmpT, lds_u8* lds, int G, int bid, int tid) {
;     ...
;         for (int l0 = 0; l0 < 32; l0 += 2) {
; #pragma unroll
;             for (int hh = 0; hh < 2; ++hh) { const int l = l0 + hh;
;                 u32x4 (&br)[4] = hh ? brB : brA;
;                 lds_u8* Bb = lds + CB + hh * CBSZ;
; #pragma unroll
;                 for (int k = 0; k < 4; ++k) { const int id = tid + 512 * k; const int col = id >> 3, c = id & 7;
;                     *(LAS u32x4*)(Bb + col * 128 + ((c ^ ((col >> 1) & 7)) * 16)) = br[k]; }
;                 __syncthreads();
;                 if (l + 2 < 32) CMP_LOADB(br, l + 2);
;                 const int arow = 16 * r32 + l;
;                 const lds_u8* ap = lds + CA + arow * 128; const int akey = (arow >> 4) & 7;
;                 const lds_u8* bp = Bb + acol * 128; const int bkey = (acol >> 1) & 7;
; #pragma unroll
;                 for (int ks = 0; ks < 4; ++ks) {
;                     const bf16x8 a = *(const LAS bf16x8*)(ap + (((2 * ks + hi) ^ akey) * 16)), bb = *(const LAS bf16x8*)(bp + (((2 * ks + hi) ^ bkey) * 16));
;                     acc = MFMA32(a, bb, acc);
;                 }
.LBB0_653:
	v_add_u32_e32 v158, s21, v87
	v_and_b32_e32 v159, 0x70, v158
	v_xad_u32 v160, v159, v89, v2
	ds_read_b128 v[160:163], v160
	v_add_u32_e32 v164, v91, v93
	ds_read_b128 v[164:167], v164
	v_xad_u32 v168, v159, v95, v2
	ds_read_b128 v[204:207], v168
	v_add_u32_e32 v168, v91, v138
	ds_read_b128 v[208:211], v168
	v_xad_u32 v168, v159, v139, v2
	ds_read_b128 v[212:215], v168
	v_add_u32_e32 v168, v91, v140
	ds_read_b128 v[216:219], v168
	v_xad_u32 v159, v159, v141, v2
	ds_read_b128 v[236:239], v159
	v_add_u32_e32 v159, v91, v142
	ds_read_b128 v[240:243], v159
	s_andn2_b64 vcc, exec, s[24:25]
	s_waitcnt lgkmcnt(6)
	v_mfma_f32_32x32x16_bf16 v[4:19], v[160:163], v[164:167], v[4:19]
	s_waitcnt lgkmcnt(4)
	v_mfma_f32_32x32x16_bf16 v[4:19], v[204:207], v[208:211], v[4:19]
	s_waitcnt lgkmcnt(2)
	v_mfma_f32_32x32x16_bf16 v[4:19], v[212:215], v[216:219], v[4:19]
	s_waitcnt vmcnt(3)
	ds_write_b128 v156, v[60:63]
	s_waitcnt vmcnt(2)
	ds_write_b128 v156, v[64:67] offset:8192
	s_waitcnt vmcnt(1)
	ds_write_b128 v156, v[76:79] offset:16384
	s_waitcnt vmcnt(0)
	ds_write_b128 v156, v[80:83] offset:24576
	s_waitcnt lgkmcnt(0)
	s_barrier
	v_mfma_f32_32x32x16_bf16 v[4:19], v[236:239], v[240:243], v[4:19]
	s_cbranch_vccnz .LBB0_650
	v_add_co_u32_e32 v60, vcc, 0x9400000, v128
	s_nop 1
	v_addc_co_u32_e32 v61, vcc, 0, v129, vcc
	v_add_co_u32_e32 v64, vcc, 0x9400000, v126
	global_load_dwordx4 v[60:63], v[60:61], off offset:384
	s_nop 0
	v_addc_co_u32_e32 v65, vcc, 0, v127, vcc
	v_add_co_u32_e32 v76, vcc, 0x9400000, v124
	global_load_dwordx4 v[64:67], v[64:65], off offset:384
	s_nop 0
	v_addc_co_u32_e32 v77, vcc, 0, v125, vcc
	v_add_co_u32_e32 v80, vcc, 0x9400000, v122
	global_load_dwordx4 v[76:79], v[76:77], off offset:384
	s_nop 0
	v_addc_co_u32_e32 v81, vcc, 0, v123, vcc
	global_load_dwordx4 v[80:83], v[80:81], off offset:384
	s_branch .LBB0_650
